# adds: static priority raise for the trailing (younger) half-workgroup across the QKV/MIN/UP GEMM K-loop
# baseline (speedup 1.0000x reference)
; #define PG8_STAGE(bufoff, gbase, voff) do { _Pragma("unroll") for (int _i = 0; _i < 2; ++_i) \
;         __builtin_amdgcn_global_load_lds((const unsigned*)((const char*)(gbase) + (voff)[_i]), (PG8_LAS unsigned*)(lds + (bufoff) + ldsw + _i * 8192), 16, 0, 0); } while (0)
; #define PG8_LDA(dst, b, h) do { _Pragma("unroll") for (int m = 0; m < 4; ++m) _Pragma("unroll") for (int k = 0; k < 2; ++k) dst[m][k] = *(const PG8_LAS bf16x8*)(lds + PG8_SA(b, h) + aoff + m * 2048 + k * 1024); } while (0)
; #define PG8_LDB(dst, b, h) do { _Pragma("unroll") for (int n = 0; n < 2; ++n) _Pragma("unroll") for (int k = 0; k < 2; ++k) dst[n][k] = *(const PG8_LAS bf16x8*)(lds + PG8_SB(b, h) + boff + n * 2048 + k * 1024); } while (0)
; #define PG8_SCHED __builtin_amdgcn_sched_barrier(0)
; template <class Epi, class Sched, bool ALIGN_EPI = false, bool SP2 = false>
; __device__ __forceinline__ void gemm_phase(PG8_LAS unsigned char* lds, const Gemm g, const Sched& S, const Epi& E) {
;     ...
;             if (last && has_next) S.a_ready(nxt);
;             if constexpr (SP2) {
;             PG8_LDB(B0, 0, 0); PG8_LDB(B1, 0, 1); PG8_SCHED; PG8_LDA(At, 0, 0); PG8_STAGE(PG8_SA(1, 1), a1 + hstep, voffA);
;     ...
; #pragma unroll
;         for (int a = 0; a < 2; ++a)
; #pragma unroll
;             for (int b = 0; b < 2; ++b)
; #pragma unroll
;                 for (int m = 0; m < 4; ++m)
; #pragma unroll
;                     for (int n = 0; n < 2; ++n) acc[a][b][m][n] = (f32x4){0.f, 0.f, 0.f, 0.f};
;         cur = nxt; cA = nA; cB = nB; ++ui;
.LBB0_353:
	s_ashr_i32 s71, s70, 31
	s_lshl_b64 s[72:73], s[70:71], 19
	s_add_u32 s72, s52, s72
	s_addc_u32 s73, s53, s73
	s_and_b64 s[74:75], s[38:39], exec
	s_cselect_b32 s1, s73, s43
	s_cselect_b32 s34, s72, s42
	s_ashr_i32 s69, s68, 31
	s_lshl_b64 s[74:75], s[68:69], 19
	s_add_u32 s74, s44, s74
	s_addc_u32 s75, s45, s75
	s_and_b64 s[88:89], s[38:39], exec
	s_cselect_b32 s41, s75, s77
	s_cselect_b32 s69, s74, s76
	s_add_u32 s42, s42, 0x40080
	s_addc_u32 s43, s43, 0
	s_add_u32 s71, s76, 0x100
	s_addc_u32 s78, s77, 0
	s_mov_b32 s88, -2
	v_mov_b64_e32 v[0:1], 0
	v_mov_b64_e32 v[2:3], 0
	v_mov_b64_e32 v[4:5], 0
	v_mov_b64_e32 v[6:7], 0
	v_mov_b64_e32 v[8:9], 0
	v_mov_b64_e32 v[10:11], 0
	v_mov_b64_e32 v[12:13], 0
	v_mov_b64_e32 v[14:15], 0
	v_mov_b64_e32 v[16:17], 0
	v_mov_b64_e32 v[18:19], 0
	v_mov_b64_e32 v[20:21], 0
	v_mov_b64_e32 v[22:23], 0
	v_mov_b64_e32 v[24:25], 0
	v_mov_b64_e32 v[26:27], 0
	v_mov_b64_e32 v[28:29], 0
	v_mov_b64_e32 v[30:31], 0
	v_mov_b64_e32 v[32:33], 0
	v_mov_b64_e32 v[34:35], 0
	v_mov_b64_e32 v[36:37], 0
	v_mov_b64_e32 v[38:39], 0
	v_mov_b64_e32 v[40:41], 0
	v_mov_b64_e32 v[42:43], 0
	v_mov_b64_e32 v[44:45], 0
	v_mov_b64_e32 v[46:47], 0
	v_mov_b64_e32 v[48:49], 0
	v_mov_b64_e32 v[50:51], 0
	v_mov_b64_e32 v[52:53], 0
	v_mov_b64_e32 v[54:55], 0
	v_mov_b64_e32 v[56:57], 0
	v_mov_b64_e32 v[58:59], 0
	v_mov_b64_e32 v[60:61], 0
	v_mov_b64_e32 v[62:63], 0
	v_mov_b64_e32 v[64:65], 0
	v_mov_b64_e32 v[66:67], 0
	v_mov_b64_e32 v[68:69], 0
	v_mov_b64_e32 v[70:71], 0
	v_mov_b64_e32 v[72:73], 0
	v_mov_b64_e32 v[74:75], 0
	v_mov_b64_e32 v[76:77], 0
	v_mov_b64_e32 v[78:79], 0
	v_mov_b64_e32 v[96:97], 0
	v_mov_b64_e32 v[98:99], 0
	v_mov_b64_e32 v[100:101], 0
	v_mov_b64_e32 v[102:103], 0
	v_mov_b64_e32 v[104:105], 0
	v_mov_b64_e32 v[106:107], 0
	v_mov_b64_e32 v[108:109], 0
	v_mov_b64_e32 v[110:111], 0
	v_mov_b64_e32 v[114:115], 0
	v_mov_b64_e32 v[116:117], 0
	v_mov_b64_e32 v[118:119], 0
	v_mov_b64_e32 v[120:121], 0
	v_mov_b64_e32 v[122:123], 0
	v_mov_b64_e32 v[124:125], 0
	v_mov_b64_e32 v[126:127], 0
	v_mov_b64_e32 v[128:129], 0
	v_mov_b64_e32 v[130:131], 0
	v_mov_b64_e32 v[132:133], 0
	v_mov_b64_e32 v[134:135], 0
	v_mov_b64_e32 v[136:137], 0
	v_mov_b64_e32 v[138:139], 0
	v_mov_b64_e32 v[140:141], 0
	v_mov_b64_e32 v[142:143], 0
	v_mov_b64_e32 v[144:145], 0
	s_cmp_lg_u32 s98, 0
	s_cbranch_scc0 .Lnp_a
	s_setprio 1
.Lnp_a:
.LBB0_354:
	s_add_u32 s2, s42, 0xfffc0080
	s_addc_u32 s76, s43, -1
	s_add_i32 s82, 0, 0x10000
	s_cmp_eq_u32 s88, 12
	s_cselect_b32 s91, s1, s76
	s_cselect_b32 s90, s34, s2
	s_cselect_b32 s77, s41, s78
	s_cselect_b32 s76, s69, s71
	s_add_i32 s2, 0, 0x14000
	v_add_u32_e32 v92, s82, v168
	v_add_u32_e32 v112, s2, v168
	ds_read_b128 v[80:83], v92
	ds_read_b128 v[84:87], v92 offset:1024
	ds_read_b128 v[88:91], v92 offset:2048
	ds_read_b128 v[92:95], v92 offset:3072
	ds_read_b128 v[160:163], v112
	ds_read_b128 v[164:167], v112 offset:1024
	ds_read_b128 v[172:175], v112 offset:2048
	ds_read_b128 v[176:179], v112 offset:3072
	s_add_i32 m0, s94, 0xc000
	ds_read_b128 v[180:183], v170
	ds_read_b128 v[184:187], v170 offset:1024
	ds_read_b128 v[192:195], v170 offset:2048
	ds_read_b128 v[196:199], v170 offset:3072
	ds_read_b128 v[200:203], v170 offset:4096
	ds_read_b128 v[204:207], v170 offset:5120
	ds_read_b128 v[208:211], v170 offset:6144
	ds_read_b128 v[212:215], v170 offset:7168
	global_load_lds_dwordx4 v156, s[42:43]
	s_add_i32 m0, s94, 0xe000
	s_nop 0
	global_load_lds_dwordx4 v158, s[42:43]
	s_cmp_lg_u32 s88, -2
	s_cbranch_scc1 .Lk0_wait
	s_cmp_gt_u32 s46, 1
	s_cbranch_scc1 .Lk0_skip

; #define PG8_STAGE(bufoff, gbase, voff) do { _Pragma("unroll") for (int _i = 0; _i < 2; ++_i) \
;         __builtin_amdgcn_global_load_lds((const unsigned*)((const char*)(gbase) + (voff)[_i]), (PG8_LAS unsigned*)(lds + (bufoff) + ldsw + _i * 8192), 16, 0, 0); } while (0)
; #define PG8_LDA(dst, b, h) do { _Pragma("unroll") for (int m = 0; m < 4; ++m) _Pragma("unroll") for (int k = 0; k < 2; ++k) dst[m][k] = *(const PG8_LAS bf16x8*)(lds + PG8_SA(b, h) + aoff + m * 2048 + k * 1024); } while (0)
; #define PG8_LDB(dst, b, h) do { _Pragma("unroll") for (int n = 0; n < 2; ++n) _Pragma("unroll") for (int k = 0; k < 2; ++k) dst[n][k] = *(const PG8_LAS bf16x8*)(lds + PG8_SB(b, h) + boff + n * 2048 + k * 1024); } while (0)
; #define PG8_MMA(ai, bj, At, Bt) do { __builtin_amdgcn_s_setprio(1); _Pragma("unroll") for (int m = 0; m < 4; ++m) _Pragma("unroll") for (int n = 0; n < 2; ++n) _Pragma("unroll") for (int k = 0; k < 2; ++k) \
;         acc[ai][bj][m][n] = __builtin_amdgcn_mfma_f32_16x16x32_bf16(Bt[n][k], At[m][k], acc[ai][bj][m][n], 0, 0, 0); __builtin_amdgcn_s_setprio(0); } while (0)
; #define PG8_WAIT_V(n) asm volatile("s_waitcnt vmcnt(" #n ")" ::: "memory")
; #define PG8_WAIT_L(n) asm volatile("s_waitcnt lgkmcnt(" #n ")" ::: "memory")
; #define PG8_BAR __builtin_amdgcn_s_barrier()
; #define PG8_SCHED __builtin_amdgcn_sched_barrier(0)
; template <class Epi, class Sched, bool ALIGN_EPI = false, bool SP2 = false>
; __device__ __forceinline__ void gemm_phase(PG8_LAS unsigned char* lds, const Gemm g, const Sched& S, const Epi& E) {
;     ...
;             PG8_LDB(B0, 0, 0); PG8_LDB(B1, 0, 1); PG8_SCHED; PG8_LDA(At, 0, 0); PG8_STAGE(PG8_SA(1, 1), a1 + hstep, voffA);
;             PG8_WAIT_V(8); PG8_WAIT_L(0); PG8_BAR; PG8_MMA(0, 0, At, B0); PG8_MMA(0, 1, At, B1); PG8_BAR; PG8_SCHED;
;             PG8_LDA(At, 0, 1); PG8_STAGE(PG8_SB(0, 0), b2, voffB); PG8_STAGE(PG8_SB(0, 1), b2 + hstep, voffB); PG8_STAGE(PG8_SA(0, 0), a2, voffA);
;             PG8_WAIT_V(8); PG8_WAIT_L(0); PG8_BAR; PG8_MMA(1, 0, At, B0); PG8_MMA(1, 1, At, B1); PG8_BAR; PG8_SCHED;
;             PG8_LDB(B0, 1, 0); PG8_LDB(B1, 1, 1); PG8_SCHED; PG8_LDA(At, 1, 0); PG8_STAGE(PG8_SA(0, 1), a2 + hstep, voffA);
;             PG8_WAIT_V(8); PG8_WAIT_L(0); PG8_BAR; PG8_MMA(0, 0, At, B0); PG8_MMA(0, 1, At, B1); PG8_BAR; PG8_SCHED;
.Lk1_skip:
	s_waitcnt lgkmcnt(0)
	s_barrier
	s_waitcnt lgkmcnt(0)
	v_mfma_f32_16x16x32_bf16 v[60:63], v[80:83], v[180:183], v[60:63]
	v_mfma_f32_16x16x32_bf16 v[56:59], v[88:91], v[180:183], v[56:59]
	v_mfma_f32_16x16x32_bf16 v[44:47], v[80:83], v[192:195], v[44:47]
	v_mfma_f32_16x16x32_bf16 v[40:43], v[88:91], v[192:195], v[40:43]
	v_mfma_f32_16x16x32_bf16 v[28:31], v[80:83], v[200:203], v[28:31]
	v_mfma_f32_16x16x32_bf16 v[24:27], v[88:91], v[200:203], v[24:27]
	v_mfma_f32_16x16x32_bf16 v[12:15], v[80:83], v[208:211], v[12:15]
	v_mfma_f32_16x16x32_bf16 v[8:11], v[88:91], v[208:211], v[8:11]
	v_mfma_f32_16x16x32_bf16 v[60:63], v[84:87], v[184:187], v[60:63]
	v_mfma_f32_16x16x32_bf16 v[56:59], v[92:95], v[184:187], v[56:59]
	v_mfma_f32_16x16x32_bf16 v[44:47], v[84:87], v[196:199], v[44:47]
	v_mfma_f32_16x16x32_bf16 v[40:43], v[92:95], v[196:199], v[40:43]
	v_mfma_f32_16x16x32_bf16 v[28:31], v[84:87], v[204:207], v[28:31]
	v_mfma_f32_16x16x32_bf16 v[24:27], v[92:95], v[204:207], v[24:27]
	v_mfma_f32_16x16x32_bf16 v[12:15], v[84:87], v[212:215], v[12:15]
	v_mfma_f32_16x16x32_bf16 v[8:11], v[92:95], v[212:215], v[8:11]
	v_mfma_f32_16x16x32_bf16 v[52:55], v[160:163], v[180:183], v[52:55]
	v_mfma_f32_16x16x32_bf16 v[48:51], v[172:175], v[180:183], v[48:51]
	v_mfma_f32_16x16x32_bf16 v[36:39], v[160:163], v[192:195], v[36:39]
	v_mfma_f32_16x16x32_bf16 v[32:35], v[172:175], v[192:195], v[32:35]
	v_mfma_f32_16x16x32_bf16 v[20:23], v[160:163], v[200:203], v[20:23]
	v_mfma_f32_16x16x32_bf16 v[16:19], v[172:175], v[200:203], v[16:19]
	v_mfma_f32_16x16x32_bf16 v[4:7], v[160:163], v[208:211], v[4:7]
	v_mfma_f32_16x16x32_bf16 v[0:3], v[172:175], v[208:211], v[0:3]
	v_mfma_f32_16x16x32_bf16 v[52:55], v[164:167], v[184:187], v[52:55]
	v_mfma_f32_16x16x32_bf16 v[48:51], v[176:179], v[184:187], v[48:51]
	v_mfma_f32_16x16x32_bf16 v[36:39], v[164:167], v[196:199], v[36:39]
	v_mfma_f32_16x16x32_bf16 v[32:35], v[176:179], v[196:199], v[32:35]
	v_mfma_f32_16x16x32_bf16 v[20:23], v[164:167], v[204:207], v[20:23]
	v_mfma_f32_16x16x32_bf16 v[16:19], v[176:179], v[204:207], v[16:19]
	v_mfma_f32_16x16x32_bf16 v[4:7], v[164:167], v[212:215], v[4:7]
	v_mfma_f32_16x16x32_bf16 v[0:3], v[176:179], v[212:215], v[0:3]
	s_barrier
	s_add_i32 s2, 0, 0x18000
	s_add_i32 s82, 0, 0x1c000
	v_add_u32_e32 v92, s2, v168
	v_add_u32_e32 v112, s82, v168
	ds_read_b128 v[80:83], v92
	ds_read_b128 v[84:87], v92 offset:1024
	ds_read_b128 v[88:91], v92 offset:2048
	ds_read_b128 v[92:95], v92 offset:3072
	ds_read_b128 v[160:163], v112
	ds_read_b128 v[164:167], v112 offset:1024
	ds_read_b128 v[172:175], v112 offset:2048
	ds_read_b128 v[176:179], v112 offset:3072
	s_add_u32 vcc_lo, s90, 0x40000
	s_addc_u32 vcc_hi, s91, 0
	s_mov_b32 m0, s96
	ds_read_b128 v[180:183], v170 offset:32768
	ds_read_b128 v[184:187], v170 offset:33792
	ds_read_b128 v[192:195], v170 offset:34816
	ds_read_b128 v[196:199], v170 offset:35840
	ds_read_b128 v[200:203], v170 offset:36864
	ds_read_b128 v[204:207], v170 offset:37888
	ds_read_b128 v[208:211], v170 offset:38912
	ds_read_b128 v[212:215], v170 offset:39936
	global_load_lds_dwordx4 v146, vcc
	s_mov_b32 m0, s97
	s_nop 0
	global_load_lds_dwordx4 v150, vcc
	s_waitcnt vmcnt(8)
	s_waitcnt lgkmcnt(0)
	s_barrier
	s_waitcnt lgkmcnt(0)
	v_mfma_f32_16x16x32_bf16 v[142:145], v[80:83], v[180:183], v[142:145]
	v_mfma_f32_16x16x32_bf16 v[138:141], v[88:91], v[180:183], v[138:141]
	v_mfma_f32_16x16x32_bf16 v[126:129], v[80:83], v[192:195], v[126:129]
	v_mfma_f32_16x16x32_bf16 v[122:125], v[88:91], v[192:195], v[122:125]
	v_mfma_f32_16x16x32_bf16 v[108:111], v[80:83], v[200:203], v[108:111]
	v_mfma_f32_16x16x32_bf16 v[104:107], v[88:91], v[200:203], v[104:107]
	v_mfma_f32_16x16x32_bf16 v[76:79], v[80:83], v[208:211], v[76:79]
	v_mfma_f32_16x16x32_bf16 v[72:75], v[88:91], v[208:211], v[72:75]
	v_mfma_f32_16x16x32_bf16 v[142:145], v[84:87], v[184:187], v[142:145]
	v_mfma_f32_16x16x32_bf16 v[138:141], v[92:95], v[184:187], v[138:141]
	v_mfma_f32_16x16x32_bf16 v[126:129], v[84:87], v[196:199], v[126:129]
	v_mfma_f32_16x16x32_bf16 v[122:125], v[92:95], v[196:199], v[122:125]
	v_mfma_f32_16x16x32_bf16 v[108:111], v[84:87], v[204:207], v[108:111]
	v_mfma_f32_16x16x32_bf16 v[104:107], v[92:95], v[204:207], v[104:107]
	v_mfma_f32_16x16x32_bf16 v[76:79], v[84:87], v[212:215], v[76:79]
	v_mfma_f32_16x16x32_bf16 v[72:75], v[92:95], v[212:215], v[72:75]
	v_mfma_f32_16x16x32_bf16 v[134:137], v[160:163], v[180:183], v[134:137]
	v_mfma_f32_16x16x32_bf16 v[130:133], v[172:175], v[180:183], v[130:133]
	v_mfma_f32_16x16x32_bf16 v[118:121], v[160:163], v[192:195], v[118:121]
	v_mfma_f32_16x16x32_bf16 v[114:117], v[172:175], v[192:195], v[114:117]
	v_mfma_f32_16x16x32_bf16 v[100:103], v[160:163], v[200:203], v[100:103]
	v_mfma_f32_16x16x32_bf16 v[96:99], v[172:175], v[200:203], v[96:99]
	v_mfma_f32_16x16x32_bf16 v[68:71], v[160:163], v[208:211], v[68:71]
	v_mfma_f32_16x16x32_bf16 v[64:67], v[172:175], v[208:211], v[64:67]
	v_mfma_f32_16x16x32_bf16 v[134:137], v[164:167], v[184:187], v[134:137]
	v_mfma_f32_16x16x32_bf16 v[130:133], v[176:179], v[184:187], v[130:133]
	v_mfma_f32_16x16x32_bf16 v[118:121], v[164:167], v[196:199], v[118:121]
	v_mfma_f32_16x16x32_bf16 v[114:117], v[176:179], v[196:199], v[114:117]
	v_mfma_f32_16x16x32_bf16 v[100:103], v[164:167], v[204:207], v[100:103]
	v_mfma_f32_16x16x32_bf16 v[96:99], v[176:179], v[204:207], v[96:99]
	v_mfma_f32_16x16x32_bf16 v[68:71], v[164:167], v[212:215], v[68:71]
	v_mfma_f32_16x16x32_bf16 v[64:67], v[176:179], v[212:215], v[64:67]
	s_barrier
; #define PG8_STAGE(bufoff, gbase, voff) do { _Pragma("unroll") for (int _i = 0; _i < 2; ++_i) \
;         __builtin_amdgcn_global_load_lds((const unsigned*)((const char*)(gbase) + (voff)[_i]), (PG8_LAS unsigned*)(lds + (bufoff) + ldsw + _i * 8192), 16, 0, 0); } while (0)
; #define PG8_LDA(dst, b, h) do { _Pragma("unroll") for (int m = 0; m < 4; ++m) _Pragma("unroll") for (int k = 0; k < 2; ++k) dst[m][k] = *(const PG8_LAS bf16x8*)(lds + PG8_SA(b, h) + aoff + m * 2048 + k * 1024); } while (0)
; #define PG8_MMA(ai, bj, At, Bt) do { __builtin_amdgcn_s_setprio(1); _Pragma("unroll") for (int m = 0; m < 4; ++m) _Pragma("unroll") for (int n = 0; n < 2; ++n) _Pragma("unroll") for (int k = 0; k < 2; ++k) \
;         acc[ai][bj][m][n] = __builtin_amdgcn_mfma_f32_16x16x32_bf16(Bt[n][k], At[m][k], acc[ai][bj][m][n], 0, 0, 0); __builtin_amdgcn_s_setprio(0); } while (0)
; #define PG8_WAIT_V(n) asm volatile("s_waitcnt vmcnt(" #n ")" ::: "memory")
; #define PG8_WAIT_L(n) asm volatile("s_waitcnt lgkmcnt(" #n ")" ::: "memory")
; #define PG8_BAR __builtin_amdgcn_s_barrier()
; #define PG8_SCHED __builtin_amdgcn_sched_barrier(0)
; template <class Epi, class Sched, bool ALIGN_EPI = false, bool SP2 = false>
; __device__ __forceinline__ void gemm_phase(PG8_LAS unsigned char* lds, const Gemm g, const Sched& S, const Epi& E) {
;     ...
;         for (int t = 0; t < nt; t += 2) {
;     ...
;             PG8_LDA(At, 1, 1); PG8_STAGE(PG8_SB(1, 0), b3, voffB); PG8_STAGE(PG8_SB(1, 1), b3 + hstep, voffB); PG8_STAGE(PG8_SA(1, 0), a3, voffA);
;             PG8_WAIT_V(8); PG8_WAIT_L(0); PG8_BAR; PG8_MMA(1, 0, At, B0); PG8_MMA(1, 1, At, B1); PG8_BAR; PG8_SCHED;
	s_add_i32 s2, s2, s55
	s_add_i32 m0, s2, 0xffffff80
	ds_read_b128 v[180:183], v170 offset:49152
	ds_read_b128 v[184:187], v170 offset:50176
	ds_read_b128 v[192:195], v170 offset:51200
	ds_read_b128 v[196:199], v170 offset:52224
	ds_read_b128 v[200:203], v170 offset:53248
	ds_read_b128 v[204:207], v170 offset:54272
	ds_read_b128 v[208:211], v170 offset:55296
	ds_read_b128 v[212:215], v170 offset:56320
	global_load_lds_dwordx4 v148, s[76:77] offset:128
	s_add_i32 m0, s2, 0x1f80
	s_add_i32 s2, s82, s55
	global_load_lds_dwordx4 v152, s[76:77] offset:128
	s_add_u32 s76, s76, 0x40080
	s_addc_u32 s77, s77, 0
	s_mov_b32 m0, s2
	s_nop 0
	global_load_lds_dwordx4 v148, s[76:77]
	s_add_i32 m0, s2, 0x2000
	s_nop 0
	global_load_lds_dwordx4 v152, s[76:77]
	s_add_i32 m0, s62, 0xffffff80
	s_nop 0
	global_load_lds_dwordx4 v146, s[90:91] offset:128
	s_add_i32 m0, s63, 0xffffff80
	s_nop 0
	global_load_lds_dwordx4 v150, s[90:91] offset:128
	s_waitcnt vmcnt(8)
	s_waitcnt lgkmcnt(0)
	s_barrier
	s_waitcnt lgkmcnt(0)
	v_mfma_f32_16x16x32_bf16 v[60:63], v[80:83], v[180:183], v[60:63]
	v_mfma_f32_16x16x32_bf16 v[56:59], v[88:91], v[180:183], v[56:59]
	v_mfma_f32_16x16x32_bf16 v[44:47], v[80:83], v[192:195], v[44:47]
	v_mfma_f32_16x16x32_bf16 v[40:43], v[88:91], v[192:195], v[40:43]
	v_mfma_f32_16x16x32_bf16 v[28:31], v[80:83], v[200:203], v[28:31]
	v_mfma_f32_16x16x32_bf16 v[24:27], v[88:91], v[200:203], v[24:27]
	v_mfma_f32_16x16x32_bf16 v[12:15], v[80:83], v[208:211], v[12:15]
	v_mfma_f32_16x16x32_bf16 v[8:11], v[88:91], v[208:211], v[8:11]
	v_mfma_f32_16x16x32_bf16 v[60:63], v[84:87], v[184:187], v[60:63]
	v_mfma_f32_16x16x32_bf16 v[56:59], v[92:95], v[184:187], v[56:59]
	v_mfma_f32_16x16x32_bf16 v[44:47], v[84:87], v[196:199], v[44:47]
	v_mfma_f32_16x16x32_bf16 v[40:43], v[92:95], v[196:199], v[40:43]
	v_mfma_f32_16x16x32_bf16 v[28:31], v[84:87], v[204:207], v[28:31]
	v_mfma_f32_16x16x32_bf16 v[24:27], v[92:95], v[204:207], v[24:27]
	v_mfma_f32_16x16x32_bf16 v[12:15], v[84:87], v[212:215], v[12:15]
	v_mfma_f32_16x16x32_bf16 v[8:11], v[92:95], v[212:215], v[8:11]
	v_mfma_f32_16x16x32_bf16 v[52:55], v[160:163], v[180:183], v[52:55]
	v_mfma_f32_16x16x32_bf16 v[48:51], v[172:175], v[180:183], v[48:51]
	v_mfma_f32_16x16x32_bf16 v[36:39], v[160:163], v[192:195], v[36:39]
	v_mfma_f32_16x16x32_bf16 v[32:35], v[172:175], v[192:195], v[32:35]
	v_mfma_f32_16x16x32_bf16 v[20:23], v[160:163], v[200:203], v[20:23]
	v_mfma_f32_16x16x32_bf16 v[16:19], v[172:175], v[200:203], v[16:19]
	v_mfma_f32_16x16x32_bf16 v[4:7], v[160:163], v[208:211], v[4:7]
	v_mfma_f32_16x16x32_bf16 v[0:3], v[172:175], v[208:211], v[0:3]
	v_mfma_f32_16x16x32_bf16 v[52:55], v[164:167], v[184:187], v[52:55]
	v_mfma_f32_16x16x32_bf16 v[48:51], v[176:179], v[184:187], v[48:51]
	v_mfma_f32_16x16x32_bf16 v[36:39], v[164:167], v[196:199], v[36:39]
	v_mfma_f32_16x16x32_bf16 v[32:35], v[176:179], v[196:199], v[32:35]
	v_mfma_f32_16x16x32_bf16 v[20:23], v[164:167], v[204:207], v[20:23]
	v_mfma_f32_16x16x32_bf16 v[16:19], v[176:179], v[204:207], v[16:19]
	v_mfma_f32_16x16x32_bf16 v[4:7], v[164:167], v[212:215], v[4:7]
	v_mfma_f32_16x16x32_bf16 v[0:3], v[176:179], v[212:215], v[0:3]
	s_barrier
	s_add_i32 s88, s88, 2
	s_add_u32 s42, s42, 0x100
	s_addc_u32 s43, s43, 0
	s_add_u32 s71, s71, 0x100
	s_addc_u32 s78, s78, 0
	s_cmp_gt_u32 s88, 13
	s_cbranch_scc0 .LBB0_354
	s_setprio 0
	s_and_b64 vcc, exec, s[66:67]
	s_cbranch_vccz .LBB0_357
	s_barrier
